# attention loop top: all 4 K-fragment and 8 V-fragment LDS reads issued up front with counted lgkmcnt
# speedup vs baseline: 1.0116x; 1.0004x over previous
; #define LAS __attribute__((address_space(3)))
; #define MFMA32(a, b, c) __builtin_amdgcn_mfma_f32_32x32x16_bf16((a), (b), (c), 0, 0, 0)
; __device__ __forceinline__ void attn_read_tile(const LAS unsigned char* buf, int lane, int q32, int g, bf16x8 (&kf)[4], bf16x8 (&vf)[2][2]) {
;     const int ki = q32 >> 3, kl = q32 & 7;
; #pragma unroll
;     for (int ks = 0; ks < 4; ++ks) kf[ks] = *(const LAS bf16x8*)(buf + ki * 1024 + (kl * 8 + ((2 * ks + g) ^ kl ^ (ki & 1))) * 16);
; #pragma unroll
;     for (int d = 0; d < 2; ++d)
; #pragma unroll
;         for (int s2 = 0; s2 < 2; ++s2) {
;             const u32x4 c0 = *(const LAS u32x4*)(buf + 4096 + (2 * s2) * 1024 + (32 * d + q32) * 16), c1 = *(const LAS u32x4*)(buf + 4096 + (2 * s2 + 1) * 1024 + (32 * d + q32) * 16);
;             const u32x4 w = {g ? c0.z : c0.x, g ? c0.w : c0.y, g ? c1.z : c1.x, g ? c1.w : c1.y}; vf[d][s2] = __builtin_bit_cast(bf16x8, w);
;         }
; __device__ __forceinline__ void attn_all(KArgs& a, LAS unsigned char* lds, int l) {
;     ...
;         auto process = [&](int t) {
;             asm volatile("s_waitcnt vmcnt(8)" ::: "memory");
;             bf16x8 kf[4], vf[2][2];
;             attn_read_tile(wbuf + (t & 1) * 8192, lane, q32, g, kf, vf);
;             f32x16 S;
; #pragma unroll
;             for (int j = 0; j < 16; ++j) S[j] = 0.f;
; #pragma unroll
;             for (int ks = 0; ks < 4; ++ks) S = MFMA32(kf[ks], qf[ks], S);
;             asm volatile("s_waitcnt lgkmcnt(0)" ::: "memory");
.LBB0_510:
	s_and_b32 s0, s9, 0x2000
	s_add_i32 s61, s19, s0
	v_add3_u32 v0, s61, v152, v153
	s_waitcnt vmcnt(8)
	v_add_u32_e32 v2, v0, v154
	ds_read_b128 v[2:5], v2 offset:16384
	v_add_u32_e32 v6, v0, v155
	ds_read_b128 v[6:9], v6 offset:16384
	v_add_u32_e32 v194, v0, v156
	ds_read_b128 v[194:197], v194 offset:16384
	v_add_u32_e32 v0, v0, v157
	ds_read_b128 v[134:137], v0 offset:16384
	v_add_u32_e32 v198, s61, v158
	ds_read_b128 v[92:95], v198 offset:20480
	ds_read_b128 v[10:13], v198 offset:20992
	ds_read_b128 v[96:99], v198 offset:21504
	ds_read_b128 v[80:83], v198 offset:22016
	ds_read_b128 v[84:87], v198 offset:22528
	ds_read_b128 v[202:205], v198 offset:23040
	ds_read_b128 v[88:91], v198 offset:23552
	ds_read_b128 v[206:209], v198 offset:24064
	s_add_i32 s0, s23, 2
	s_min_i32 s63, s0, s60
	s_cmp_ge_i32 s0, s58
	s_mov_b64 s[0:1], -1
	s_waitcnt lgkmcnt(10)
	v_mfma_f32_32x32x16_bf16 v[48:63], v[2:5], v[72:75], 0
	v_mfma_f32_32x32x16_bf16 v[48:63], v[6:9], v[64:67], v[48:63]
	s_waitcnt lgkmcnt(8)
	v_mfma_f32_32x32x16_bf16 v[48:63], v[194:197], v[68:71], v[48:63]
	v_mfma_f32_32x32x16_bf16 v[48:63], v[134:137], v[76:79], v[48:63]
	s_waitcnt lgkmcnt(0)
	s_cbranch_scc0 .LBB0_512
	s_sub_i32 s0, s63, s58
	s_lshl_b32 s62, s0, 5
	s_mov_b64 s[0:1], 0

; __device__ __forceinline__ unsigned pk2(float lo, float hi) { const f32x2 v = {lo, hi}; return __builtin_bit_cast(unsigned, __builtin_convertvector(v, bf16v2_t)); }
; #define MFMA32(a, b, c) __builtin_amdgcn_mfma_f32_32x32x16_bf16((a), (b), (c), 0, 0, 0)
; __device__ __forceinline__ void attn_read_tile(const LAS unsigned char* buf, int lane, int q32, int g, bf16x8 (&kf)[4], bf16x8 (&vf)[2][2]) {
;     ...
;             const u32x4 w = {g ? c0.z : c0.x, g ? c0.w : c0.y, g ? c1.z : c1.x, g ? c1.w : c1.y}; vf[d][s2] = __builtin_bit_cast(bf16x8, w);
; __device__ __forceinline__ void attn_all(KArgs& a, LAS unsigned char* lds, int l) {
;     ...
;             float p[16], ps = 0.f;
; #pragma unroll
;             for (int j = 0; j < 16; ++j) { p[j] = __builtin_amdgcn_exp2f(sv[j] - mrun); ps += p[j]; }
;             lsum += ps;
;             const u32x4 w0 = {pk2(p[0], p[1]), pk2(p[2], p[3]), pk2(p[4], p[5]), pk2(p[6], p[7])}, w1 = {pk2(p[8], p[9]), pk2(p[10], p[11]), pk2(p[12], p[13]), pk2(p[14], p[15])};
;             const bf16x8 pb0 = __builtin_bit_cast(bf16x8, w0), pb1 = __builtin_bit_cast(bf16x8, w1);
;             O0 = MFMA32(vf[0][0], pb0, O0); O0 = MFMA32(vf[0][1], pb1, O0);
;             O1 = MFMA32(vf[1][0], pb0, O1); O1 = MFMA32(vf[1][1], pb1, O1);
.LBB0_521:
	v_sub_f32_e32 v14, v14, v0
	v_exp_f32_e32 v14, v14
	v_sub_f32_e32 v15, v15, v0
	v_exp_f32_e32 v15, v15
	v_sub_f32_e32 v48, v134, v0
	v_exp_f32_e32 v55, v48
	v_sub_f32_e32 v48, v135, v0
	v_add_f32_e32 v49, 0, v14
	v_exp_f32_e32 v56, v48
	v_sub_f32_e32 v48, v136, v0
	v_add_f32_e32 v49, v15, v49
	v_exp_f32_e32 v57, v48
	v_sub_f32_e32 v48, v137, v0
	v_exp_f32_e32 v58, v48
	v_add_f32_e32 v48, v55, v49
	v_sub_f32_e32 v49, v138, v0
	v_exp_f32_e32 v49, v49
	v_sub_f32_e32 v50, v139, v0
	v_add_f32_e32 v48, v56, v48
	v_exp_f32_e32 v59, v50
	v_sub_f32_e32 v50, v140, v0
	v_add_f32_e32 v48, v57, v48
	v_exp_f32_e32 v60, v50
	v_sub_f32_e32 v50, v141, v0
	v_add_f32_e32 v48, v58, v48
	v_exp_f32_e32 v61, v50
	v_add_f32_e32 v48, v49, v48
	v_add_f32_e32 v48, v59, v48
	v_cndmask_b32_e64 v10, v12, v10, s[40:41]
	v_cndmask_b32_e64 v50, v94, v92, s[40:41]
	v_cndmask_b32_e64 v51, v95, v93, s[40:41]
	v_cndmask_b32_e64 v52, v98, v96, s[40:41]
	v_cndmask_b32_e64 v53, v99, v97, s[40:41]
	v_cndmask_b32_e64 v11, v13, v11, s[40:41]
	v_cndmask_b32_e64 v12, v82, v80, s[40:41]
	v_cndmask_b32_e64 v13, v83, v81, s[40:41]
	v_add_f32_e32 v48, v60, v48
	v_add_f32_e32 v62, v61, v48
	v_sub_f32_e32 v48, v142, v0
	v_exp_f32_e32 v63, v48
	v_sub_f32_e32 v48, v143, v0
	v_exp_f32_e32 v134, v48
	v_sub_f32_e32 v48, v144, v0
	v_cvt_pk_bf16_f32 v54, v14, v15
	v_cvt_pk_bf16_f32 v55, v55, v56
	v_cvt_pk_bf16_f32 v56, v57, v58
	v_cvt_pk_bf16_f32 v57, v49, v59
	v_exp_f32_e32 v135, v48
	v_sub_f32_e32 v48, v145, v0
	v_mfma_f32_32x32x16_bf16 v[32:47], v[50:53], v[54:57], v[32:47]
	v_exp_f32_e32 v136, v48
	v_sub_f32_e32 v48, v146, v0
	v_exp_f32_e32 v137, v48
	v_sub_f32_e32 v48, v147, v0
	v_exp_f32_e32 v138, v48
	v_cndmask_b32_e64 v48, v86, v84, s[40:41]
	v_cndmask_b32_e64 v49, v87, v85, s[40:41]
	v_mfma_f32_32x32x16_bf16 v[16:31], v[10:13], v[54:57], v[16:31]
	v_cndmask_b32_e64 v50, v90, v88, s[40:41]
	v_cndmask_b32_e64 v51, v91, v89, s[40:41]
	v_cndmask_b32_e64 v2, v204, v202, s[40:41]
	v_cndmask_b32_e64 v3, v205, v203, s[40:41]
	v_cndmask_b32_e64 v4, v208, v206, s[40:41]
	v_cndmask_b32_e64 v5, v209, v207, s[40:41]
	v_cvt_pk_bf16_f32 v58, v60, v61
	v_cvt_pk_bf16_f32 v59, v63, v134
	v_cvt_pk_bf16_f32 v60, v135, v136
	v_cvt_pk_bf16_f32 v61, v137, v138
	v_add_f32_e32 v14, v63, v62
	v_add_f32_e32 v14, v134, v14
	v_mfma_f32_32x32x16_bf16 v[32:47], v[48:51], v[58:61], v[32:47]
	v_add_f32_e32 v14, v135, v14
	v_add_f32_e32 v6, v136, v14
	v_add_f32_e32 v6, v137, v6
	v_add_f32_e32 v6, v138, v6
	s_add_i32 s23, s23, 1
	s_addk_i32 s9, 0x2000
	v_add_f32_e32 v107, v107, v6
	v_mfma_f32_32x32x16_bf16 v[16:31], v[2:5], v[58:61], v[16:31]
	s_cmp_eq_u32 s8, s23
	v_add_u32_e32 v109, 0x7c, v109
	s_cbranch_scc1 .LBB0_492
	v_mov_b32_e32 v160, v0
	s_branch .LBB0_510
